# v47 + EpiUp: n=1 halo loads (sites 2/3) also issued at the epilogue top into free quads, copied in place later
# baseline (speedup 1.0000x reference)
;     __device__ __forceinline__ void operator()(Acc& acc, const Unit& u, int wr, int wc, int fr, int fq, LAS unsigned char* lds, int tid) const {
;     ...
;             const unsigned colp = u.pn * 256 + bj * 128 + wc * 32 + 8 * fq;
;             const unsigned coll = bj * FF + u.pn * 128 + wc * 32 + 8 * fq;
; #pragma unroll
;             for (int n = 0; n < 2; ++n) {
;                 f32x4 c0 = ldf4(cw, coll + 4u * n), c1 = ldf4(cw, (unsigned)FF2 + coll + 4u * n), c2 = ldf4(cw, 2u * FF2 + coll + 4u * n);
;                 if constexpr (I8) { const f32x4 swv = ldf4(sw, colp + 4u * n); c0 = c0 * swv; c1 = c1 * swv; c2 = c2 * swv; }
;                 f32x4 hl = {0.f, 0.f, 0.f, 0.f}, hr = {0.f, 0.f, 0.f, 0.f};
;                 if (fr == 0 && lvalid) hl = ldf4(HALO, (2u * bk) * (unsigned)FF2 + colp + 4u * n);
;                 if (fr == 15 && rvalid) hr = ldf4(HALO, (2u * bk + 1u) * (unsigned)FF2 + colp + 4u * n);
.LBB0_1072:
	s_or_b64 exec, exec, s[60:61]
	v_or_b32_e32 v214, 0x80, v177
	v_add_u32_e32 v182, s1, v214
	v_add_u32_e32 v183, s0, v214
	v_lshlrev_b32_e32 v182, 2, v182
	v_lshlrev_b32_e32 v183, 2, v183
	s_cmp_lg_u64 s[44:45], 0
	s_cbranch_scc1 .Lzs_4e
	v_mov_b32_e32 v184, 0
	v_mov_b32_e32 v185, 0
	v_mov_b32_e32 v186, 0
	v_mov_b32_e32 v187, 0

;     __device__ __forceinline__ void operator()(Acc& acc, const Unit& u, int wr, int wc, int fr, int fq, LAS unsigned char* lds, int tid) const {
;     ...
;             for (int ai = 0; ai < 2; ++ai) { const f32x4 sa = ldf4(sx, tok0 + tl0 + 4u * ai);
; #pragma unroll
;                 for (int m = 0; m < 4; ++m)
; #pragma unroll
;                     for (int bj = 0; bj < 2; ++bj)
; #pragma unroll
;                         for (int n = 0; n < 2; ++n) { const pg8::i32x4 iv = __builtin_bit_cast(pg8::i32x4, acc[ai][bj][m][n]); acc[ai][bj][m][n] = __builtin_convertvector(iv, f32x4) * sa[m]; }
;                 asm volatile("" ::: "memory"); }
;         }
;         const unsigned bk = 2 * u.pm + wr;
;         const bool lvalid = (bk & 15) != 0, rvalid = (bk & 15) != 15;
; #pragma unroll
;         for (int bj = 0; bj < 2; ++bj) {
;             const unsigned colp = u.pn * 256 + bj * 128 + wc * 32 + 8 * fq;
;             const unsigned coll = bj * FF + u.pn * 128 + wc * 32 + 8 * fq;
; #pragma unroll
;             for (int n = 0; n < 2; ++n) {
;                 f32x4 c0 = ldf4(cw, coll + 4u * n), c1 = ldf4(cw, (unsigned)FF2 + coll + 4u * n), c2 = ldf4(cw, 2u * FF2 + coll + 4u * n);
;                 if constexpr (I8) { const f32x4 swv = ldf4(sw, colp + 4u * n); c0 = c0 * swv; c1 = c1 * swv; c2 = c2 * swv; }
;                 f32x4 hl = {0.f, 0.f, 0.f, 0.f}, hr = {0.f, 0.f, 0.f, 0.f};
;                 if (fr == 0 && lvalid) hl = ldf4(HALO, (2u * bk) * (unsigned)FF2 + colp + 4u * n);
;                 if (fr == 15 && rvalid) hr = ldf4(HALO, (2u * bk + 1u) * (unsigned)FF2 + colp + 4u * n);
.Lzs_5e:
	s_and_saveexec_b64 s[60:61], vcc
	global_load_dwordx4 v[204:207], v183, s[38:39]
	s_or_b64 exec, exec, s[60:61]
	v_lshl_or_b32 v182, v172, 2, 16
	v_lshl_or_b32 v183, v178, 2, 16
	s_cmp_lg_u64 s[44:45], 0
	s_cbranch_scc1 .Lzs_2e
	v_mov_b32_e32 v238, 0
	v_mov_b32_e32 v239, 0
	v_mov_b32_e32 v240, 0
	v_mov_b32_e32 v241, 0
.Lzs_2e:
	s_and_saveexec_b64 s[60:61], s[44:45]
	global_load_dwordx4 v[238:241], v182, s[38:39]
	s_or_b64 exec, exec, s[60:61]
	s_cbranch_vccnz .Lzs_3e
	v_mov_b32_e32 v242, 0
	v_mov_b32_e32 v243, 0
	v_mov_b32_e32 v244, 0
	v_mov_b32_e32 v245, 0
.Lzs_3e:
	s_and_saveexec_b64 s[60:61], vcc
	global_load_dwordx4 v[242:245], v183, s[38:39]
	s_or_b64 exec, exec, s[60:61]
	v_mov_b32_e32 v147, v209
	v_lshl_add_u64 v[180:181], s[28:29], 0, v[146:147]
	v_cvt_f32_i32_e32 v147, v161
	v_cvt_f32_i32_e32 v146, v160
	v_cvt_f32_i32_e32 v161, v163
	v_cvt_f32_i32_e32 v160, v162
	v_lshl_add_u64 v[164:165], s[22:23], 0, v[208:209]
	v_cvt_f32_i32_e32 v149, v149
	v_cvt_f32_i32_e32 v148, v148
	v_cvt_f32_i32_e32 v153, v153
	v_cvt_f32_i32_e32 v152, v152
	v_cvt_f32_i32_e32 v155, v155
	v_cvt_f32_i32_e32 v154, v154
	v_cvt_f32_i32_e32 v151, v151
	v_cvt_f32_i32_e32 v150, v150
	v_cvt_f32_i32_e32 v117, v117
	v_cvt_f32_i32_e32 v116, v116
	v_cvt_f32_i32_e32 v109, v109
	v_cvt_f32_i32_e32 v108, v108
	v_cvt_f32_i32_e32 v119, v119
	v_cvt_f32_i32_e32 v118, v118
	v_cvt_f32_i32_e32 v111, v111
	v_cvt_f32_i32_e32 v110, v110
	v_cvt_f32_i32_e32 v53, v53
	v_cvt_f32_i32_e32 v52, v52
	v_cvt_f32_i32_e32 v49, v49
	v_cvt_f32_i32_e32 v48, v48
	v_cvt_f32_i32_e32 v45, v45
	v_cvt_f32_i32_e32 v44, v44
	v_cvt_f32_i32_e32 v41, v41
	v_cvt_f32_i32_e32 v40, v40
	v_cvt_f32_i32_e32 v37, v37
	v_cvt_f32_i32_e32 v36, v36
	v_cvt_f32_i32_e32 v33, v33
	v_cvt_f32_i32_e32 v32, v32
	v_cvt_f32_i32_e32 v55, v55
	v_cvt_f32_i32_e32 v54, v54
	v_cvt_f32_i32_e32 v51, v51
	v_cvt_f32_i32_e32 v50, v50
	v_cvt_f32_i32_e32 v47, v47
	v_cvt_f32_i32_e32 v46, v46
	v_cvt_f32_i32_e32 v43, v43
	v_cvt_f32_i32_e32 v42, v42
	v_cvt_f32_i32_e32 v39, v39
	v_cvt_f32_i32_e32 v38, v38
	v_cvt_f32_i32_e32 v27, v27
	v_cvt_f32_i32_e32 v26, v26
	v_cvt_f32_i32_e32 v13, v13
	v_cvt_f32_i32_e32 v12, v12
	v_cvt_f32_i32_e32 v35, v35
	v_cvt_f32_i32_e32 v34, v34
	v_cvt_f32_i32_e32 v101, v101
	v_cvt_f32_i32_e32 v100, v100
	v_cvt_f32_i32_e32 v97, v97
	v_cvt_f32_i32_e32 v96, v96
	v_cvt_f32_i32_e32 v93, v93
	v_cvt_f32_i32_e32 v92, v92
	v_cvt_f32_i32_e32 v11, v11
	v_cvt_f32_i32_e32 v10, v10
	v_cvt_f32_i32_e32 v89, v89
	v_cvt_f32_i32_e32 v88, v88
	v_cvt_f32_i32_e32 v31, v31
	v_cvt_f32_i32_e32 v30, v30
	v_cvt_f32_i32_e32 v17, v17
	v_cvt_f32_i32_e32 v16, v16
	v_cvt_f32_i32_e32 v85, v85
	v_cvt_f32_i32_e32 v84, v84
	v_cvt_f32_i32_e32 v77, v77
	v_cvt_f32_i32_e32 v79, v79
	v_cvt_f32_i32_e32 v78, v78
	v_cvt_f32_i32_e32 v76, v76
	v_cvt_f32_i32_e32 v57, v57
	v_cvt_f32_i32_e32 v59, v59
	v_cvt_f32_i32_e32 v58, v58
	v_cvt_f32_i32_e32 v56, v56
	v_cvt_f32_i32_e32 v7, v7
	v_cvt_f32_i32_e32 v6, v6
	v_cvt_f32_i32_e32 v103, v103
	v_cvt_f32_i32_e32 v102, v102
	v_cvt_f32_i32_e32 v99, v99
	v_cvt_f32_i32_e32 v98, v98
	v_cvt_f32_i32_e32 v95, v95
	v_cvt_f32_i32_e32 v94, v94
	v_cvt_f32_i32_e32 v91, v91
	v_cvt_f32_i32_e32 v90, v90
	v_cvt_f32_i32_e32 v87, v87
	v_cvt_f32_i32_e32 v86, v86
	v_cvt_f32_i32_e32 v81, v81
	v_cvt_f32_i32_e32 v80, v80
	v_cvt_f32_i32_e32 v73, v73
	v_cvt_f32_i32_e32 v72, v72
	v_cvt_f32_i32_e32 v69, v69
	v_cvt_f32_i32_e32 v68, v68
	v_cvt_f32_i32_e32 v65, v65
	v_cvt_f32_i32_e32 v64, v64
	v_cvt_f32_i32_e32 v61, v61
	v_cvt_f32_i32_e32 v60, v60
	v_cvt_f32_i32_e32 v83, v83
	v_cvt_f32_i32_e32 v82, v82
	v_cvt_f32_i32_e32 v67, v67
	v_cvt_f32_i32_e32 v66, v66
	v_cvt_f32_i32_e32 v63, v63
	v_cvt_f32_i32_e32 v62, v62
	v_cvt_f32_i32_e32 v29, v29
	v_cvt_f32_i32_e32 v28, v28
	v_cvt_f32_i32_e32 v25, v25
	v_cvt_f32_i32_e32 v24, v24
	v_cvt_f32_i32_e32 v19, v19
	v_cvt_f32_i32_e32 v18, v18
	v_cvt_f32_i32_e32 v15, v15
	v_cvt_f32_i32_e32 v14, v14
	v_cvt_f32_i32_e32 v75, v75
	v_cvt_f32_i32_e32 v74, v74
	v_cvt_f32_i32_e32 v23, v23
	v_cvt_f32_i32_e32 v22, v22
	v_cvt_f32_i32_e32 v21, v21
	v_cvt_f32_i32_e32 v20, v20
	v_cvt_f32_i32_e32 v71, v71
	v_cvt_f32_i32_e32 v70, v70
	s_waitcnt vmcnt(9)
;     __device__ bool next(int i, Unit& u) const { return S.next(i, u); }
;     __device__ bool next(int i, Unit& u) const { const int L = i * G + c; if (L >= 3 * 44) return false; u.pm = L % 3; u.pn = L / 3; u.g = 0; u.part = 0; u.keep = 0; return true; }
;     __device__ __forceinline__ void operator()(Acc& acc, const Unit& u, int wr, int wc, int fr, int fq, LAS unsigned char* lds, int tid) const {
;     ...
;                 f32x4 c0 = ldf4(cw, coll + 4u * n), c1 = ldf4(cw, (unsigned)FF2 + coll + 4u * n), c2 = ldf4(cw, 2u * FF2 + coll + 4u * n);
;                 if constexpr (I8) { const f32x4 swv = ldf4(sw, colp + 4u * n); c0 = c0 * swv; c1 = c1 * swv; c2 = c2 * swv; }
;                 f32x4 hl = {0.f, 0.f, 0.f, 0.f}, hr = {0.f, 0.f, 0.f, 0.f};
;                 if (fr == 0 && lvalid) hl = ldf4(HALO, (2u * bk) * (unsigned)FF2 + colp + 4u * n);
;                 if (fr == 15 && rvalid) hr = ldf4(HALO, (2u * bk + 1u) * (unsigned)FF2 + colp + 4u * n);
; #pragma unroll
;                 for (int e = 0; e < 4; ++e) {
;                     const float prev = dpp_shr1(hl[e], acc[1][bj][3][n][e]);
;                     const float next = dpp_shl1(hr[e], acc[0][bj][0][n][e]);
;                     float left = prev;
; #pragma unroll
;                     for (int j = 0; j < 8; ++j) {
;                         const float cur = acc[j >> 2][bj][j & 3][n][e];
;                         const float nx = (j < 7) ? acc[(j + 1) >> 2][bj][(j + 1) & 3][n][e] : next;
;                         acc[j >> 2][bj][j & 3][n][e] = c0[e] * left + c1[e] * cur + c2[e] * nx;
	v_pk_mul_f32 v[224:225], v[112:113], v[146:147] op_sel_hi:[0,1]
	v_cvt_f32_i32_e32 v147, v157
	v_cvt_f32_i32_e32 v146, v156
	v_cvt_f32_i32_e32 v157, v159
	v_cvt_f32_i32_e32 v156, v158
	s_waitcnt vmcnt(8)
	v_mov_b32_e32 v158, v107
	v_add_u32_e32 v145, 0xb010, v208
	v_pk_mul_f32 v[220:221], v[112:113], v[160:161] op_sel_hi:[0,1]
	v_pk_mul_f32 v[218:219], v[158:159], v[156:157] op_sel_hi:[0,1]
	v_pk_mul_f32 v[222:223], v[158:159], v[146:147] op_sel_hi:[0,1]
	global_load_dwordx4 v[160:163], v[164:165], off offset:16
	global_load_dwordx4 v[156:159], v145, s[22:23]
	v_add_u32_e32 v145, 0x16010, v208
	global_load_dwordx4 v[164:167], v145, s[22:23]
	global_load_dwordx4 v[168:171], v[180:181], off offset:16
	s_waitcnt vmcnt(8)
	v_mov_b32_dpp v120, v222 row_shr:1 row_mask:0xf bank_mask:0xf
	v_mov_b32_dpp v124, v224 row_shl:1 row_mask:0xf bank_mask:0xf
	v_mov_b32_dpp v121, v223 row_shr:1 row_mask:0xf bank_mask:0xf
	v_mov_b32_dpp v125, v225 row_shl:1 row_mask:0xf bank_mask:0xf
	v_mov_b32_dpp v122, v218 row_shr:1 row_mask:0xf bank_mask:0xf
	v_mov_b32_dpp v126, v220 row_shl:1 row_mask:0xf bank_mask:0xf
	v_mov_b32_dpp v123, v219 row_shr:1 row_mask:0xf bank_mask:0xf
	v_mov_b32_dpp v127, v221 row_shl:1 row_mask:0xf bank_mask:0xf
	s_waitcnt vmcnt(4)
	v_mov_b32_e32 v144, v238
	v_mov_b32_e32 v145, v239
	v_mov_b32_e32 v146, v240
	v_mov_b32_e32 v147, v241
	v_mov_b32_e32 v172, v242
	v_mov_b32_e32 v173, v243
	v_mov_b32_e32 v174, v244
	v_mov_b32_e32 v175, v245
	v_mov_b32_e32 v226, v107
	v_mov_b32_e32 v227, v107
	v_pk_mul_f32 v[234:235], v[226:227], v[148:149]
	v_add_u32_e32 v149, 0x5800, v208
	global_load_dwordx4 v[188:191], v149, s[22:23]
	v_add_u32_e32 v149, 0x10800, v208
	v_or_b32_e32 v148, 0x80, v177
	global_load_dwordx4 v[196:199], v149, s[22:23]
	v_add_u32_e32 v149, 0x1b800, v208
	global_load_dwordx4 v[192:195], v149, s[22:23]
	v_lshlrev_b32_e32 v149, 2, v148
	global_load_dwordx4 v[200:203], v149, s[28:29]
	v_mov_b32_e32 v228, v112
	v_mov_b32_e32 v229, v112
	v_mov_b32_e32 v178, v112
	v_mov_b32_e32 v179, v112
	v_pk_mul_f32 v[236:237], v[228:229], v[152:153]
	v_mov_b32_e32 v152, v107
	v_mov_b32_e32 v153, v107
	v_pk_mul_f32 v[232:233], v[178:179], v[154:155]
	v_pk_mul_f32 v[230:231], v[152:153], v[150:151]
	s_waitcnt vmcnt(4)
	v_mov_b32_dpp v144, v234 row_shr:1 row_mask:0xf bank_mask:0xf
	v_mov_b32_dpp v172, v236 row_shl:1 row_mask:0xf bank_mask:0xf
	v_mov_b32_dpp v145, v235 row_shr:1 row_mask:0xf bank_mask:0xf
	v_mov_b32_dpp v173, v237 row_shl:1 row_mask:0xf bank_mask:0xf
	v_mov_b32_dpp v146, v230 row_shr:1 row_mask:0xf bank_mask:0xf
	v_mov_b32_dpp v174, v232 row_shl:1 row_mask:0xf bank_mask:0xf
	v_mov_b32_dpp v147, v231 row_shr:1 row_mask:0xf bank_mask:0xf
	v_mov_b32_dpp v175, v233 row_shl:1 row_mask:0xf bank_mask:0xf
	v_add_u32_e32 v215, s1, v148
	v_add_u32_e32 v216, s0, v148
	v_mov_b32_e32 v148, 0
	v_mov_b32_e32 v150, v112
	v_mov_b32_e32 v151, v112
	v_pk_mul_f32 v[244:245], v[228:229], v[116:117]
	v_mov_b32_e32 v116, v107
	v_mov_b32_e32 v117, v107
	v_pk_mul_f32 v[242:243], v[226:227], v[108:109]
	v_add_u32_e32 v108, 0x5810, v208
	v_pk_mul_f32 v[240:241], v[150:151], v[118:119]
	v_pk_mul_f32 v[238:239], v[116:117], v[110:111]
	s_waitcnt vmcnt(11)
	v_mov_b32_e32 v176, v184
	v_mov_b32_e32 v177, v185
	v_mov_b32_e32 v178, v186
	v_mov_b32_e32 v179, v187
	global_load_dwordx4 v[116:119], v108, s[22:23]
	v_add_u32_e32 v108, 0x10810, v208
	global_load_dwordx4 v[184:187], v108, s[22:23]
	v_add_u32_e32 v108, 0x1b810, v208
	global_load_dwordx4 v[152:155], v108, s[22:23]
	s_nop 0
	global_load_dwordx4 v[180:183], v[180:181], off offset:528
	s_waitcnt vmcnt(4)
	v_mov_b32_dpp v176, v242 row_shr:1 row_mask:0xf bank_mask:0xf
	v_mov_b32_dpp v204, v244 row_shl:1 row_mask:0xf bank_mask:0xf
	v_mov_b32_dpp v177, v243 row_shr:1 row_mask:0xf bank_mask:0xf
	v_mov_b32_dpp v205, v245 row_shl:1 row_mask:0xf bank_mask:0xf
	v_mov_b32_dpp v178, v238 row_shr:1 row_mask:0xf bank_mask:0xf
	v_mov_b32_dpp v206, v240 row_shl:1 row_mask:0xf bank_mask:0xf
	v_mov_b32_dpp v179, v239 row_shr:1 row_mask:0xf bank_mask:0xf
	v_mov_b32_dpp v207, v241 row_shl:1 row_mask:0xf bank_mask:0xf
	s_cmp_lg_u64 s[44:45], 0
	s_cbranch_scc1 .Lzs_6
	v_mov_b32_e32 v149, 0
	v_mov_b32_e32 v150, 0
	v_mov_b32_e32 v151, 0
